# DA barrier-rotation stagger regrouped: group = parity of wave-id bits 0 and 2, so the two waves of a SIMD are in different groups under either wave-to-SIMD dealing
# speedup vs baseline: 1.0006x; 1.0006x over previous
; DI unsigned cvtpk(float lo, float hi) { f32x2_t v = {lo, hi}; bf16x2_t b = __builtin_convertvector(v, bf16x2_t); return __builtin_bit_cast(unsigned, b); }
; #define MFMA32(a, b, c) __builtin_amdgcn_mfma_f32_32x32x16_bf16((a), (b), (c), 0, 0, 0)
; #define SBAR() __builtin_amdgcn_sched_barrier(0)
; template <int VSTR, int NDVB> DI void pv64(f32x16 (&O)[NDVB], const lds8* vp, const bf16x8 (&P)[4]) {
;   bf16x8 f[2][NDVB];
; #pragma unroll
;   for (int d = 0; d < NDVB; ++d) { const s16x4 lo = trrd(vp + d * 64), hi = trrd(vp + 8 * VSTR + d * 64); f[0][d] = __builtin_shufflevector(lo, hi, 0, 1, 2, 3, 4, 5, 6, 7); }
; #pragma unroll
;   for (int kk = 0; kk < 4; ++kk) {
;     if (kk < 3) {
; #pragma unroll
;       for (int d = 0; d < NDVB; ++d) { const s16x4 lo = trrd(vp + (16 * (kk + 1)) * VSTR + d * 64), hi = trrd(vp + (16 * (kk + 1) + 8) * VSTR + d * 64);
;         f[(kk + 1) & 1][d] = __builtin_shufflevector(lo, hi, 0, 1, 2, 3, 4, 5, 6, 7); }
;     }
;     SBAR();
;     __builtin_amdgcn_s_setprio(1);
; #pragma unroll
;     for (int d = 0; d < NDVB; ++d) O[d] = MFMA32(f[kk & 1][d], P[kk], O[d]);
;     __builtin_amdgcn_s_setprio(0);
;     SBAR();
;   }
; }
; template <int NDVB, bool HAS_NEXT> DI void softmax_def(f32x16& sa0, f32x16& sa1, f32x16& sb0, f32x16& sb1, f32x16 (&O)[NDVB], float& muse, float& l, bool first, bf16x8 (&P)[4], bool check = true) {
;     ...
;   for (int i = 0; i < 16; ++i) { sa0[i] = __builtin_amdgcn_exp2f(sa0[i]); sum += sa0[i]; }
; #pragma unroll
;   for (int i = 0; i < 16; ++i) { sa1[i] = __builtin_amdgcn_exp2f(sa1[i]); sum += sa1[i]; }
;   l += sum;
;   u32x4 w;
;   w.x = cvtpk(sa0[0], sa0[1]); w.y = cvtpk(sa0[2], sa0[3]); w.z = cvtpk(sa0[4], sa0[5]); w.w = cvtpk(sa0[6], sa0[7]); P[0] = __builtin_bit_cast(bf16x8, w);
;   w.x = cvtpk(sa0[8], sa0[9]); w.y = cvtpk(sa0[10], sa0[11]); w.z = cvtpk(sa0[12], sa0[13]); w.w = cvtpk(sa0[14], sa0[15]); P[1] = __builtin_bit_cast(bf16x8, w);
;   w.x = cvtpk(sa1[0], sa1[1]); w.y = cvtpk(sa1[2], sa1[3]); w.z = cvtpk(sa1[4], sa1[5]); w.w = cvtpk(sa1[6], sa1[7]); P[2] = __builtin_bit_cast(bf16x8, w);
;   w.x = cvtpk(sa1[8], sa1[9]); w.y = cvtpk(sa1[10], sa1[11]); w.z = cvtpk(sa1[12], sa1[13]); w.w = cvtpk(sa1[14], sa1[15]); P[3] = __builtin_bit_cast(bf16x8, w);
.LBB0_851:
	s_nop 3
	v_add_u32_e32 v145, s20, v140
	v_add_u32_e32 v145, 0xffffbcc0, v145
	ds_read_b64_tr_b16 v[232:233], v145 offset:0
	ds_read_b64_tr_b16 v[234:235], v145 offset:2432
	ds_read_b64_tr_b16 v[236:237], v145 offset:64
	ds_read_b64_tr_b16 v[238:239], v145 offset:2496
	ds_read_b64_tr_b16 v[240:241], v145 offset:128
	ds_read_b64_tr_b16 v[242:243], v145 offset:2560
	ds_read_b64_tr_b16 v[244:245], v145 offset:192
	ds_read_b64_tr_b16 v[246:247], v145 offset:2624
	ds_read_b64_tr_b16 v[146:147], v145 offset:4864
	ds_read_b64_tr_b16 v[148:149], v145 offset:7296
	ds_read_b64_tr_b16 v[150:151], v145 offset:4928
	ds_read_b64_tr_b16 v[152:153], v145 offset:7360
	ds_read_b64_tr_b16 v[154:155], v145 offset:4992
	ds_read_b64_tr_b16 v[156:157], v145 offset:7424
	ds_read_b64_tr_b16 v[192:193], v145 offset:5056
	ds_read_b64_tr_b16 v[194:195], v145 offset:7488
	s_mul_i32 s21, s21, 3
	s_add_i32 s21, s21, -1
	v_exp_f32_e32 v96, v96
	v_exp_f32_e32 v97, v97
	v_exp_f32_e32 v98, v98
	v_exp_f32_e32 v99, v99
	v_exp_f32_e32 v100, v100
	v_exp_f32_e32 v101, v101
	v_exp_f32_e32 v102, v102
	v_exp_f32_e32 v103, v103
	v_cvt_pk_bf16_f32 v216, v96, v97
	v_cvt_pk_bf16_f32 v217, v98, v99
	v_cvt_pk_bf16_f32 v218, v100, v101
	v_cvt_pk_bf16_f32 v219, v102, v103
	v_readfirstlane_b32 s22, v200
	s_nop 1
	s_and_b32 s22, s22, 0x140
	s_bcnt1_i32_b32 s22, s22
	s_bitcmp1_b32 s22, 0
	s_cbranch_scc0 .Lda_nobar_b
	s_barrier

; DI int crow(int i, int h) { return (i & 3) + 8 * (i >> 2) + 4 * h; }
; template <bool LOAD2, bool MASK>
; DI void da_step(lds8* lds, const DaCtx& cx, int t, const bf16x8 (&q)[4], f32x16 (&O)[4], float& muse, float& l, f32x16& negm) {
;     ...
;   const int st = t % 3, stn2 = (st == 0) ? 2 : st - 1;
;   const bool cur_live = !MASK || 64 * t <= cx.q0 + 32 * cx.qs + 31;
;   if (cur_live) {
;     f32x16 sa0, sa1, du0, du1;
;     qk64c<DA_KSTR>(sa0, sa1, lds + st * DA_STAGE + cx.koff, q, negm);
;     if (MASK) {
;       if (64 * t + 63 > cx.q0 + 32 * cx.qs) {
; #pragma unroll
;         for (int i = 0; i < 16; ++i) { const int key = 64 * t + crow(i, cx.h); if (key > cx.qpos) sa0[i] = NEG; if (key + 32 > cx.qpos) sa1[i] = NEG; }
;       }
;     }
;     bf16x8 P[4];
;     const float mprev = muse;
;     softmax_def<4, false>(sa0, sa1, du0, du1, O, muse, l, t == 0, P, MASK || (t & 1) == 0);
;     if (__any(muse != mprev)) {
; #pragma unroll
;       for (int i = 0; i < 16; ++i) negm[i] = -muse;
;     }
;     pv64<DA_KSTR, 4>(O, lds + st * DA_STAGE + cx.voff, P);
.Lda_negm_same:
	s_setprio 0
	s_add_i32 s20, s10, s20
	s_cmp_lg_u32 s21, s12
	s_cselect_b32 s12, s20, 0x13000
	s_add_i32 s12, s12, 0
	s_add_i32 s11, s11, 1
	s_add_i32 s10, s10, 0x9800
	v_add3_u32 v80, s12, v137, v186
	v_add3_u32 v81, s12, v138, v186
	v_readfirstlane_b32 s20, v200
	s_nop 1
	s_and_b32 s20, s20, 0x140
	s_bcnt1_i32_b32 s20, s20
	s_bitcmp1_b32 s20, 0
	s_cbranch_scc1 .Lda_nobar_a
	s_barrier
